# v25 plus: no store drain in front of the closing barrier of the N=1024 GEMM phases (the epilogue loads already retired the trailing LDS-DMA), no vmcnt(0) between the two P5 GEMMs
# speedup vs baseline: 1.0166x; 1.0043x over previous
; #define PG8_WAIT_V(n) asm volatile("s_waitcnt vmcnt(" #n ")" ::: "memory")
; #define PG8_BAR __builtin_amdgcn_s_barrier()
; template <class Epi, class Sched, bool ALIGN_EPI = false, bool SP2 = false>
; __device__ __forceinline__ void gemm_phase(PG8_LAS unsigned char* lds, const Gemm g, const Sched& S, const Epi& E) {
;     ...
;     PG8_WAIT_V(0);
;     if constexpr (!ALIGN_EPI) { if (wr == 0) PG8_BAR; }
;     PG8_BAR;
.LBB0_185:
	s_nop 0
	s_barrier

; #define VM_WAIT() asm volatile("s_waitcnt vmcnt(0)" ::: "memory")
; __global__ void __launch_bounds__(NWAVES * 64, 2) mk_fwd(Args args) {
;     ...
;       { pg8::Gemm g{(const bf16*)(ws + WS_ZA), (const bf16*)(ws + WS_WA), TP, DM, DA}; pg8::StaticOrder S; S.init(TP, DM, F.G, (int)blockIdx.x);
;         pg8::EpiGate<0> E{(const bf16*)(ws + WS_SGA), (bf16*)(ws + WS_MG)}; pg8::gemm_phase<pg8::EpiGate<0>, pg8::StaticOrder, true, true>(F.lds, g, S, E); }
;       VM_WAIT();
;       { pg8::Gemm g{(const bf16*)(ws + WS_BG), (const bf16*)(ws + WS_WB), TP, DM, DA}; pg8::StaticOrder S; S.init(TP, DM, F.G, (int)blockIdx.x);
;         pg8::EpiGate<1> E{(const bf16*)(ws + WS_SGB), (bf16*)(ws + WS_MG)}; pg8::gemm_phase<pg8::EpiGate<1>, pg8::StaticOrder, true, true>(F.lds, g, S, E); }
.LBB0_1584:
	s_add_u32 s36, s22, 0x9780000
	s_addc_u32 s37, s23, 0
	s_add_u32 s38, s22, 0xd00000
	s_nop 0
	s_addc_u32 s39, s23, 0
	s_add_u32 s16, s22, 0x6480000
	s_addc_u32 s17, s23, 0
	s_andn2_b64 vcc, exec, s[40:41]
	v_readfirstlane_b32 s44, v0
	s_cbranch_vccnz .LBB0_1608
	s_ashr_i32 s3, s2, 31
	s_lshr_b32 s6, s3, 29
	s_add_i32 s19, s2, s6
	s_and_b32 s6, s19, -8
	s_sub_i32 s41, s2, s6
	s_cmp_gt_i32 s41, -1
	s_cbranch_scc0 .LBB0_1587
	s_lshl_b32 s40, s41, 5
	s_cbranch_execz .LBB0_1588
	s_branch .LBB0_1589
